# dead t0/t1 64-bit division chains before the P0 tile loop removed (tile ranges come from the per-batch split)
# speedup vs baseline: 1.0104x; 1.0033x over previous
.LBB0_26:
	v_readlane_b32 s68, v251, 22
	v_readlane_b32 s69, v251, 23
	s_mov_b32 s9, 0
	s_mov_b32 s11, 0
.LBB0_33:
.LBB0_34:
	s_cmp_lg_u32 s100, 0
	s_cbranch_scc1 .Lp0_go
	s_lshr_b32 s0, s83, 6
	s_and_b32 s1, s83, 63
	s_movk_i32 s4, 0
	s_movk_i32 s5, 0
	s_cmp_eq_u32 s0, 1
	s_cselect_b32 s4, 2, s4
	s_cselect_b32 s5, 0, s5
	s_cmp_eq_u32 s0, 2
	s_cselect_b32 s4, 3, s4
	s_cselect_b32 s5, 128, s5
	s_cmp_eq_u32 s0, 3
	s_cselect_b32 s4, 3, s4
	s_cselect_b32 s5, 320, s5
	s_mul_i32 s6, s1, s4
	s_add_i32 s8, s5, s6
	s_add_i32 s10, s8, s4
